# carry: all eight LDS fragment reads of a chunk issued right after the barrier into their own registers, MFMAs with counted lgkmcnt (on top of the padded tile)
# baseline (speedup 1.0000x reference)
; #define LAS __attribute__((address_space(3)))
; #define CARRY_LOAD(Q, C) do { const float* pc_ = PC + cb0 + (size_t)(C) * 4096 + g4 * 64 + ct * 16 + fr; \
;                 _Pragma("unroll") for (int kk = 0; kk < 16; ++kk) pr[Q][kk] = pc_[kk * 256]; \
;                 const float* lc_ = LC + cb0 + (size_t)(C) * 4096 + (size_t)(r0 + g4 * 4) * 64 + ct * 16 + fr; \
;                 lr[Q] = (f32x4c){lc_[0], lc_[64], lc_[128], lc_[192]}; } while (0)
; __device__ __forceinline__ void even_carry(const Params& p, int j, LAS unsigned char* lds, const int wave_s) {
;     ...
;             CARRY_LOAD(0, 0); CARRY_LOAD(1, 1); CARRY_LOAD(2, 2); CARRY_LOAD(3, 3);
;             f32x4c d = (f32x4c){0.f, 0.f, 0.f, 0.f};
;             for (int c4 = 0; c4 < NCH; c4 += 4) {
; #pragma unroll
;                 for (int q = 0; q < 4; ++q) {
;                     const int c = c4 + q;
;                     float* sst = SST + cb0 + (size_t)c * 4096 + (size_t)(r0 + g4 * 4) * 64 + ct * 16 + fr;
;                     LAS float* sb = Ss + (c & 1) * 1024;
; #pragma unroll
;                     for (int r = 0; r < 4; ++r) { sst[r * 64] = d[r]; sb[(g4 * 4 + r) * 64 + ct * 16 + fr] = d[r]; }
;                     __syncthreads();
;                     f32x4c acc = lr[q];
; #pragma unroll
;                     for (int kk = 0; kk < 16; ++kk) acc = __builtin_amdgcn_mfma_f32_16x16x4f32(sb[fr * 64 + kk * 4 + g4], pr[q][kk], acc, 0, 0, 0);
;                     d = acc;
;                     if (c + 4 < NCH) CARRY_LOAD(q, c + 4);
.LBB0_1436:
	v_lshl_add_u64 v[36:37], v[34:35], 0, v[22:23]
	s_mov_b32 s2, 0x3db00000
	v_add_co_u32_e32 v38, vcc, s2, v36
	s_cmp_lt_u32 s24, 28
	s_nop 0
	v_addc_co_u32_e32 v39, vcc, 0, v37, vcc
	global_store_dword v[38:39], v16, off
	global_store_dword v[38:39], v17, off offset:256
	ds_write2_b32 v40, v16, v17 offset1:68
	global_store_dword v[38:39], v18, off offset:512
	global_store_dword v[38:39], v19, off offset:768
	ds_write2_b32 v40, v18, v19 offset0:136 offset1:204
	s_waitcnt lgkmcnt(0)
	s_barrier
	ds_read2_b32 v[110:111], v31 offset1:4
	ds_read2_b32 v[112:113], v31 offset0:8 offset1:12
	ds_read2_b32 v[114:115], v31 offset0:16 offset1:20
	ds_read2_b32 v[116:117], v31 offset0:24 offset1:28
	ds_read2_b32 v[118:119], v31 offset0:32 offset1:36
	ds_read2_b32 v[120:121], v31 offset0:40 offset1:44
	ds_read2_b32 v[122:123], v31 offset0:48 offset1:52
	ds_read2_b32 v[124:125], v31 offset0:56 offset1:60
	s_waitcnt vmcnt(16) lgkmcnt(7)
	v_mfma_f32_16x16x4_f32 v[16:19], v110, v27, v[0:3]
	s_cselect_b64 s[12:13], -1, 0
	s_cmp_gt_u32 s24, 27
	s_cselect_b64 s[2:3], -1, 0
	s_and_b64 vcc, exec, s[2:3]
	v_mfma_f32_16x16x4_f32 v[16:19], v111, v41, v[16:19]
	s_waitcnt lgkmcnt(6)
	v_mfma_f32_16x16x4_f32 v[16:19], v112, v42, v[16:19]
	v_mfma_f32_16x16x4_f32 v[16:19], v113, v43, v[16:19]
	s_waitcnt lgkmcnt(5)
	v_mfma_f32_16x16x4_f32 v[16:19], v114, v44, v[16:19]
	v_mfma_f32_16x16x4_f32 v[16:19], v115, v45, v[16:19]
	s_waitcnt lgkmcnt(4)
	v_mfma_f32_16x16x4_f32 v[16:19], v116, v46, v[16:19]
	v_mfma_f32_16x16x4_f32 v[16:19], v117, v47, v[16:19]
	s_waitcnt lgkmcnt(3)
	v_mfma_f32_16x16x4_f32 v[16:19], v118, v48, v[16:19]
	v_mfma_f32_16x16x4_f32 v[16:19], v119, v49, v[16:19]
	s_waitcnt lgkmcnt(2)
	v_mfma_f32_16x16x4_f32 v[16:19], v120, v50, v[16:19]
	v_mfma_f32_16x16x4_f32 v[16:19], v121, v51, v[16:19]
	s_waitcnt lgkmcnt(1)
	v_mfma_f32_16x16x4_f32 v[16:19], v122, v52, v[16:19]
	v_mfma_f32_16x16x4_f32 v[16:19], v123, v53, v[16:19]
	s_waitcnt lgkmcnt(0)
	v_mfma_f32_16x16x4_f32 v[16:19], v124, v54, v[16:19]
	v_mfma_f32_16x16x4_f32 v[16:19], v125, v55, v[16:19]
	v_lshl_add_u64 v[38:39], v[32:33], 0, v[22:23]
	s_cbranch_vccnz .LBB0_1438
	v_add_co_u32_e32 v0, vcc, 0x3b910000, v38
	s_nop 1
	v_addc_co_u32_e32 v1, vcc, 0, v39, vcc
	v_add_co_u32_e32 v2, vcc, 0x3b911000, v38
	s_nop 1
	v_addc_co_u32_e32 v3, vcc, 0, v39, vcc
	global_load_dword v27, v[0:1], off
	global_load_dword v41, v[0:1], off offset:1024
	global_load_dword v42, v[0:1], off offset:2048
	global_load_dword v43, v[0:1], off offset:3072
	global_load_dword v44, v[2:3], off
	global_load_dword v45, v[2:3], off offset:1024
	global_load_dword v46, v[2:3], off offset:2048
	global_load_dword v47, v[2:3], off offset:3072
	v_add_co_u32_e32 v0, vcc, 0x3b912000, v38
	s_nop 1
	v_addc_co_u32_e32 v1, vcc, 0, v39, vcc
	v_add_co_u32_e32 v2, vcc, 0x3b913000, v38
	s_nop 1
	v_addc_co_u32_e32 v3, vcc, 0, v39, vcc
	global_load_dword v48, v[0:1], off
	global_load_dword v49, v[0:1], off offset:1024
	global_load_dword v50, v[0:1], off offset:2048
	global_load_dword v51, v[0:1], off offset:3072
	global_load_dword v52, v[2:3], off
	global_load_dword v53, v[2:3], off offset:1024
	global_load_dword v54, v[2:3], off offset:2048
	global_load_dword v55, v[2:3], off offset:3072
	v_add_co_u32_e32 v104, vcc, 0x39710000, v36
	s_nop 1
	v_addc_co_u32_e32 v105, vcc, 0, v37, vcc
	global_load_dword v0, v[104:105], off
	global_load_dword v1, v[104:105], off offset:256
	global_load_dword v2, v[104:105], off offset:512
	global_load_dword v3, v[104:105], off offset:768
.LBB0_1438:
	s_mov_b32 s25, 0x3db04000
	v_add_co_u32_e32 v104, vcc, s25, v36
	v_add_u32_e32 v103, 0x1100, v31
	s_nop 0
	v_addc_co_u32_e32 v105, vcc, 0, v37, vcc
	s_nop 2
	global_store_dword v[104:105], v16, off
	global_store_dword v[104:105], v17, off offset:256
	ds_write2_b32 v106, v16, v17 offset1:68
	global_store_dword v[104:105], v18, off offset:512
	global_store_dword v[104:105], v19, off offset:768
	ds_write2_b32 v106, v18, v19 offset0:136 offset1:204
	s_waitcnt lgkmcnt(0)
	s_barrier
	ds_read2_b32 v[110:111], v103 offset1:4
	ds_read2_b32 v[112:113], v103 offset0:8 offset1:12
	ds_read2_b32 v[114:115], v103 offset0:16 offset1:20
	ds_read2_b32 v[116:117], v103 offset0:24 offset1:28
	ds_read2_b32 v[118:119], v103 offset0:32 offset1:36
	ds_read2_b32 v[120:121], v103 offset0:40 offset1:44
	ds_read2_b32 v[122:123], v103 offset0:48 offset1:52
	ds_read2_b32 v[124:125], v103 offset0:56 offset1:60
	s_waitcnt vmcnt(16) lgkmcnt(7)
	v_mfma_f32_16x16x4_f32 v[16:19], v110, v29, v[4:7]
	s_andn2_b64 vcc, exec, s[12:13]
	v_mfma_f32_16x16x4_f32 v[16:19], v111, v56, v[16:19]
	s_waitcnt lgkmcnt(6)
	v_mfma_f32_16x16x4_f32 v[16:19], v112, v57, v[16:19]
	v_mfma_f32_16x16x4_f32 v[16:19], v113, v58, v[16:19]
	s_waitcnt lgkmcnt(5)
	v_mfma_f32_16x16x4_f32 v[16:19], v114, v59, v[16:19]
	v_mfma_f32_16x16x4_f32 v[16:19], v115, v60, v[16:19]
	s_waitcnt lgkmcnt(4)
	v_mfma_f32_16x16x4_f32 v[16:19], v116, v61, v[16:19]
	v_mfma_f32_16x16x4_f32 v[16:19], v117, v62, v[16:19]
	s_waitcnt lgkmcnt(3)
	v_mfma_f32_16x16x4_f32 v[16:19], v118, v63, v[16:19]
	v_mfma_f32_16x16x4_f32 v[16:19], v119, v64, v[16:19]
	s_waitcnt lgkmcnt(2)
	v_mfma_f32_16x16x4_f32 v[16:19], v120, v65, v[16:19]
	v_mfma_f32_16x16x4_f32 v[16:19], v121, v66, v[16:19]
	s_waitcnt lgkmcnt(1)
	v_mfma_f32_16x16x4_f32 v[16:19], v122, v67, v[16:19]
	v_mfma_f32_16x16x4_f32 v[16:19], v123, v68, v[16:19]
	s_waitcnt lgkmcnt(0)
	v_mfma_f32_16x16x4_f32 v[16:19], v124, v69, v[16:19]
	v_cndmask_b32_e64 v104, 0, 1, s[12:13]
	v_cmp_ne_u32_e64 s[38:39], 1, v104
	v_mfma_f32_16x16x4_f32 v[16:19], v125, v70, v[16:19]
	s_cbranch_vccnz .LBB0_1440
	v_add_co_u32_e32 v4, vcc, 0x3b914000, v38
	s_nop 1
	v_addc_co_u32_e32 v5, vcc, 0, v39, vcc
	v_add_co_u32_e32 v6, vcc, 0x3b915000, v38
	s_nop 1
	v_addc_co_u32_e32 v7, vcc, 0, v39, vcc
	global_load_dword v29, v[4:5], off
	global_load_dword v56, v[4:5], off offset:1024
	global_load_dword v57, v[4:5], off offset:2048
	global_load_dword v58, v[4:5], off offset:3072
	global_load_dword v59, v[6:7], off
	global_load_dword v60, v[6:7], off offset:1024
	global_load_dword v61, v[6:7], off offset:2048
	global_load_dword v62, v[6:7], off offset:3072
	v_add_co_u32_e32 v4, vcc, 0x3b916000, v38
	s_nop 1
	v_addc_co_u32_e32 v5, vcc, 0, v39, vcc
	v_add_co_u32_e32 v6, vcc, 0x3b917000, v38
	s_nop 1
	v_addc_co_u32_e32 v7, vcc, 0, v39, vcc
	global_load_dword v63, v[4:5], off
	global_load_dword v64, v[4:5], off offset:1024
	global_load_dword v65, v[4:5], off offset:2048
	global_load_dword v66, v[4:5], off offset:3072
	global_load_dword v67, v[6:7], off
	global_load_dword v68, v[6:7], off offset:1024
	global_load_dword v69, v[6:7], off offset:2048
	global_load_dword v70, v[6:7], off offset:3072
	v_add_co_u32_e32 v104, vcc, 0x39714000, v36
	s_nop 1
	v_addc_co_u32_e32 v105, vcc, 0, v37, vcc
	global_load_dword v4, v[104:105], off
	global_load_dword v5, v[104:105], off offset:256
	global_load_dword v6, v[104:105], off offset:512
	global_load_dword v7, v[104:105], off offset:768
; #define LAS __attribute__((address_space(3)))
; #define CARRY_LOAD(Q, C) do { const float* pc_ = PC + cb0 + (size_t)(C) * 4096 + g4 * 64 + ct * 16 + fr; \
;                 _Pragma("unroll") for (int kk = 0; kk < 16; ++kk) pr[Q][kk] = pc_[kk * 256]; \
;                 const float* lc_ = LC + cb0 + (size_t)(C) * 4096 + (size_t)(r0 + g4 * 4) * 64 + ct * 16 + fr; \
;                 lr[Q] = (f32x4c){lc_[0], lc_[64], lc_[128], lc_[192]}; } while (0)
; __device__ __forceinline__ void even_carry(const Params& p, int j, LAS unsigned char* lds, const int wave_s) {
;     ...
;             CARRY_LOAD(0, 0); CARRY_LOAD(1, 1); CARRY_LOAD(2, 2); CARRY_LOAD(3, 3);
;             f32x4c d = (f32x4c){0.f, 0.f, 0.f, 0.f};
;             for (int c4 = 0; c4 < NCH; c4 += 4) {
; #pragma unroll
;                 for (int q = 0; q < 4; ++q) {
;                     const int c = c4 + q;
;                     float* sst = SST + cb0 + (size_t)c * 4096 + (size_t)(r0 + g4 * 4) * 64 + ct * 16 + fr;
;                     LAS float* sb = Ss + (c & 1) * 1024;
; #pragma unroll
;                     for (int r = 0; r < 4; ++r) { sst[r * 64] = d[r]; sb[(g4 * 4 + r) * 64 + ct * 16 + fr] = d[r]; }
;                     __syncthreads();
;                     f32x4c acc = lr[q];
; #pragma unroll
;                     for (int kk = 0; kk < 16; ++kk) acc = __builtin_amdgcn_mfma_f32_16x16x4f32(sb[fr * 64 + kk * 4 + g4], pr[q][kk], acc, 0, 0, 0);
;                     d = acc;
;                     if (c + 4 < NCH) CARRY_LOAD(q, c + 4);
.LBB0_1440:
	s_mov_b32 s12, 0x3db08000
	v_add_co_u32_e32 v104, vcc, s12, v36
	s_nop 1
	v_addc_co_u32_e32 v105, vcc, 0, v37, vcc
	s_nop 3
	global_store_dword v[104:105], v16, off
	global_store_dword v[104:105], v17, off offset:256
	ds_write2_b32 v40, v16, v17 offset1:68
	global_store_dword v[104:105], v18, off offset:512
	global_store_dword v[104:105], v19, off offset:768
	ds_write2_b32 v40, v18, v19 offset0:136 offset1:204
	s_waitcnt lgkmcnt(0)
	s_barrier
	ds_read2_b32 v[110:111], v31 offset1:4
	ds_read2_b32 v[112:113], v31 offset0:8 offset1:12
	ds_read2_b32 v[114:115], v31 offset0:16 offset1:20
	ds_read2_b32 v[116:117], v31 offset0:24 offset1:28
	ds_read2_b32 v[118:119], v31 offset0:32 offset1:36
	ds_read2_b32 v[120:121], v31 offset0:40 offset1:44
	ds_read2_b32 v[122:123], v31 offset0:48 offset1:52
	ds_read2_b32 v[124:125], v31 offset0:56 offset1:60
	s_waitcnt vmcnt(16) lgkmcnt(7)
	v_mfma_f32_16x16x4_f32 v[16:19], v110, v71, v[8:11]
	s_and_b64 vcc, exec, s[38:39]
	v_mfma_f32_16x16x4_f32 v[16:19], v111, v72, v[16:19]
	s_waitcnt lgkmcnt(6)
	v_mfma_f32_16x16x4_f32 v[16:19], v112, v73, v[16:19]
	v_mfma_f32_16x16x4_f32 v[16:19], v113, v74, v[16:19]
	s_waitcnt lgkmcnt(5)
	v_mfma_f32_16x16x4_f32 v[16:19], v114, v75, v[16:19]
	v_mfma_f32_16x16x4_f32 v[16:19], v115, v76, v[16:19]
	s_waitcnt lgkmcnt(4)
	v_mfma_f32_16x16x4_f32 v[16:19], v116, v77, v[16:19]
	v_mfma_f32_16x16x4_f32 v[16:19], v117, v78, v[16:19]
	s_waitcnt lgkmcnt(3)
	v_mfma_f32_16x16x4_f32 v[16:19], v118, v79, v[16:19]
	v_mfma_f32_16x16x4_f32 v[16:19], v119, v80, v[16:19]
	s_waitcnt lgkmcnt(2)
	v_mfma_f32_16x16x4_f32 v[16:19], v120, v81, v[16:19]
	v_mfma_f32_16x16x4_f32 v[16:19], v121, v82, v[16:19]
	s_waitcnt lgkmcnt(1)
	v_mfma_f32_16x16x4_f32 v[16:19], v122, v86, v[16:19]
	v_mfma_f32_16x16x4_f32 v[16:19], v123, v88, v[16:19]
	s_waitcnt lgkmcnt(0)
	v_mfma_f32_16x16x4_f32 v[16:19], v124, v89, v[16:19]
	v_mfma_f32_16x16x4_f32 v[16:19], v125, v90, v[16:19]
	s_cbranch_vccnz .LBB0_1442
	v_add_co_u32_e32 v8, vcc, 0x3b918000, v38
	s_nop 1
	v_addc_co_u32_e32 v9, vcc, 0, v39, vcc
	v_add_co_u32_e32 v10, vcc, 0x3b919000, v38
	s_nop 1
	v_addc_co_u32_e32 v11, vcc, 0, v39, vcc
	global_load_dword v71, v[8:9], off
	global_load_dword v72, v[8:9], off offset:1024
	global_load_dword v73, v[8:9], off offset:2048
	global_load_dword v74, v[8:9], off offset:3072
	global_load_dword v75, v[10:11], off
	global_load_dword v76, v[10:11], off offset:1024
	global_load_dword v77, v[10:11], off offset:2048
	global_load_dword v78, v[10:11], off offset:3072
	v_add_co_u32_e32 v8, vcc, 0x3b91a000, v38
	s_nop 1
	v_addc_co_u32_e32 v9, vcc, 0, v39, vcc
	v_add_co_u32_e32 v10, vcc, 0x3b91b000, v38
	s_nop 1
	v_addc_co_u32_e32 v11, vcc, 0, v39, vcc
	global_load_dword v79, v[8:9], off
	global_load_dword v80, v[8:9], off offset:1024
	global_load_dword v81, v[8:9], off offset:2048
	global_load_dword v82, v[8:9], off offset:3072
	global_load_dword v86, v[10:11], off
	global_load_dword v88, v[10:11], off offset:1024
	global_load_dword v89, v[10:11], off offset:2048
	global_load_dword v90, v[10:11], off offset:3072
	v_add_co_u32_e32 v104, vcc, 0x39718000, v36
	s_nop 1
	v_addc_co_u32_e32 v105, vcc, 0, v37, vcc
	global_load_dword v8, v[104:105], off
	global_load_dword v9, v[104:105], off offset:256
	global_load_dword v10, v[104:105], off offset:512
	global_load_dword v11, v[104:105], off offset:768
.LBB0_1442:
	s_mov_b32 s12, 0x3db0c000
	v_add_co_u32_e32 v104, vcc, s12, v36
	s_nop 1
	v_addc_co_u32_e32 v105, vcc, 0, v37, vcc
	s_nop 3
	global_store_dword v[104:105], v16, off
	global_store_dword v[104:105], v17, off offset:256
	ds_write2_b32 v106, v16, v17 offset1:68
	global_store_dword v[104:105], v18, off offset:512
	global_store_dword v[104:105], v19, off offset:768
	ds_write2_b32 v106, v18, v19 offset0:136 offset1:204
	s_waitcnt lgkmcnt(0)
	s_barrier
	ds_read2_b32 v[110:111], v103 offset1:4
	ds_read2_b32 v[112:113], v103 offset0:8 offset1:12
	ds_read2_b32 v[114:115], v103 offset0:16 offset1:20
	ds_read2_b32 v[116:117], v103 offset0:24 offset1:28
	ds_read2_b32 v[118:119], v103 offset0:32 offset1:36
	ds_read2_b32 v[120:121], v103 offset0:40 offset1:44
	ds_read2_b32 v[122:123], v103 offset0:48 offset1:52
	ds_read2_b32 v[124:125], v103 offset0:56 offset1:60
	s_waitcnt vmcnt(16) lgkmcnt(7)
	v_mfma_f32_16x16x4_f32 v[16:19], v110, v83, v[12:15]
	s_and_b64 vcc, exec, s[38:39]
	v_mfma_f32_16x16x4_f32 v[16:19], v111, v84, v[16:19]
	s_waitcnt lgkmcnt(6)
	v_mfma_f32_16x16x4_f32 v[16:19], v112, v85, v[16:19]
	v_mfma_f32_16x16x4_f32 v[16:19], v113, v87, v[16:19]
	s_waitcnt lgkmcnt(5)
	v_mfma_f32_16x16x4_f32 v[16:19], v114, v91, v[16:19]
	v_mfma_f32_16x16x4_f32 v[16:19], v115, v92, v[16:19]
	s_waitcnt lgkmcnt(4)
	v_mfma_f32_16x16x4_f32 v[16:19], v116, v93, v[16:19]
	v_mfma_f32_16x16x4_f32 v[16:19], v117, v94, v[16:19]
	s_waitcnt lgkmcnt(3)
	v_mfma_f32_16x16x4_f32 v[16:19], v118, v95, v[16:19]
	v_mfma_f32_16x16x4_f32 v[16:19], v119, v96, v[16:19]
	s_waitcnt lgkmcnt(2)
	v_mfma_f32_16x16x4_f32 v[16:19], v120, v97, v[16:19]
	v_mfma_f32_16x16x4_f32 v[16:19], v121, v98, v[16:19]
	s_waitcnt lgkmcnt(1)
	v_mfma_f32_16x16x4_f32 v[16:19], v122, v99, v[16:19]
	v_mfma_f32_16x16x4_f32 v[16:19], v123, v100, v[16:19]
	s_waitcnt lgkmcnt(0)
	v_mfma_f32_16x16x4_f32 v[16:19], v124, v101, v[16:19]
	v_mfma_f32_16x16x4_f32 v[16:19], v125, v102, v[16:19]
	s_cbranch_vccnz .LBB0_1435
	v_add_co_u32_e32 v12, vcc, 0x3b91c000, v38
	s_nop 1
	v_addc_co_u32_e32 v13, vcc, 0, v39, vcc
	global_load_dword v83, v[12:13], off
	global_load_dword v84, v[12:13], off offset:1024
	global_load_dword v85, v[12:13], off offset:2048
	global_load_dword v87, v[12:13], off offset:3072
	v_add_co_u32_e32 v12, vcc, 0x3b91d000, v38
	s_nop 1
	v_addc_co_u32_e32 v13, vcc, 0, v39, vcc
	global_load_dword v91, v[12:13], off
	global_load_dword v92, v[12:13], off offset:1024
	global_load_dword v93, v[12:13], off offset:2048
	global_load_dword v94, v[12:13], off offset:3072
	v_add_co_u32_e32 v12, vcc, 0x3b91e000, v38
	s_nop 1
	v_addc_co_u32_e32 v13, vcc, 0, v39, vcc
	global_load_dword v95, v[12:13], off
	global_load_dword v96, v[12:13], off offset:1024
	global_load_dword v97, v[12:13], off offset:2048
	global_load_dword v98, v[12:13], off offset:3072
	v_add_co_u32_e32 v12, vcc, 0x3b91f000, v38
	s_nop 1
	v_addc_co_u32_e32 v13, vcc, 0, v39, vcc
	v_add_co_u32_e32 v36, vcc, 0x3971c000, v36
	global_load_dword v99, v[12:13], off
	global_load_dword v100, v[12:13], off offset:1024
	global_load_dword v101, v[12:13], off offset:2048
	global_load_dword v102, v[12:13], off offset:3072
	v_addc_co_u32_e32 v37, vcc, 0, v37, vcc
	global_load_dword v12, v[36:37], off
	global_load_dword v13, v[36:37], off offset:256
	global_load_dword v14, v[36:37], off offset:512
	global_load_dword v15, v[36:37], off offset:768
	s_branch .LBB0_1435
